# ssq phase and its grid barrier removed: y phase writes per-head row sums of squares, out-proj GEMM tile header reduces them into LDS
# speedup vs baseline: 1.0219x; 1.0080x over previous
.LBB0_2102:
	v_readlane_b32 s22, v252, 12
	v_readlane_b32 s23, v252, 13
	v_lshlrev_b32_e32 v96, 1, v173
	s_lshl_b64 s[14:15], s[22:23], 2
	v_readlane_b32 s16, v252, 51
	v_lshl_or_b32 v96, s22, 7, v96
	v_mov_b32_e32 v97, v129
	s_add_u32 s14, s16, s14
	v_readlane_b32 s16, v252, 52
	v_lshl_add_u64 v[112:113], v[184:185], 0, v[96:97]
	s_addc_u32 s15, s16, s15
	global_load_dword v118, v129, s[14:15]
	v_readlane_b32 s19, v255, 57
	v_add_u32_e32 v245, 0x2000, v205
	ds_read2_b64 v[186:189], v205 offset1:2
	ds_read2_b64 v[190:193], v205 offset0:4 offset1:6
	ds_read2_b64 v[194:197], v245 offset0:64 offset1:66
	ds_read2_b64 v[206:209], v245 offset0:68 offset1:70
	s_add_i32 s19, s19, 1
	s_mov_b64 s[14:15], 0x1000
	v_lshl_add_u64 v[100:101], v[112:113], 0, s[14:15]
	s_mov_b64 s[14:15], 0x3000
	v_lshl_add_u64 v[102:103], v[112:113], 0, s[14:15]
	s_mov_b64 s[14:15], 0x9000
	v_lshl_add_u64 v[104:105], v[112:113], 0, s[14:15]
	s_mov_b64 s[14:15], 0xb000
	v_lshl_add_u64 v[106:107], v[112:113], 0, s[14:15]
	s_mov_b64 s[14:15], 0x11000
	v_lshl_add_u64 v[108:109], v[112:113], 0, s[14:15]
	s_mov_b64 s[14:15], 0x13000
	v_lshl_add_u64 v[110:111], v[112:113], 0, s[14:15]
	s_mov_b64 s[14:15], 0x19000
	v_lshl_add_u64 v[114:115], v[112:113], 0, s[14:15]
	s_mov_b64 s[14:15], 0x1b000
	v_lshl_add_u64 v[116:117], v[112:113], 0, s[14:15]
	global_load_ushort v96, v[100:101], off offset:-4096
	global_load_ushort v97, v[100:101], off
	global_load_ushort v98, v[102:103], off offset:-4096
	global_load_ushort v99, v[102:103], off
	global_load_ushort v119, v[104:105], off offset:-4096
	global_load_ushort v120, v[104:105], off
	global_load_ushort v121, v[106:107], off offset:-4096
	global_load_ushort v122, v[106:107], off
	global_load_ushort v123, v[108:109], off offset:-4096
	global_load_ushort v124, v[108:109], off
	global_load_ushort v125, v[110:111], off offset:-4096
	global_load_ushort v126, v[110:111], off
	global_load_ushort v127, v[114:115], off offset:-4096
	global_load_ushort v212, v[114:115], off
	global_load_ushort v213, v[116:117], off offset:-4096
	global_load_ushort v214, v[116:117], off
	global_load_ushort v215, v[100:101], off offset:-4032
	global_load_ushort v222, v[100:101], off offset:64
	global_load_ushort v223, v[102:103], off offset:-4032
	global_load_ushort v224, v[102:103], off offset:64
	global_load_ushort v225, v[104:105], off offset:-4032
	global_load_ushort v234, v[104:105], off offset:64
	global_load_ushort v235, v[106:107], off offset:-4032
	global_load_ushort v236, v[106:107], off offset:64
	global_load_ushort v237, v[108:109], off offset:-4032
	global_load_ushort v238, v[108:109], off offset:64
	global_load_ushort v239, v[110:111], off offset:-4032
	global_load_ushort v240, v[110:111], off offset:64
	global_load_ushort v241, v[114:115], off offset:-4032
	global_load_ushort v242, v[114:115], off offset:64
	global_load_ushort v243, v[116:117], off offset:-4032
	global_load_ushort v244, v[116:117], off offset:64
	s_waitcnt lgkmcnt(0)
	s_waitcnt vmcnt(28)
	v_lshlrev_b32_e32 v96, 16, v96
	v_lshlrev_b32_e32 v97, 16, v97
	v_lshlrev_b32_e32 v98, 16, v98
	v_lshlrev_b32_e32 v99, 16, v99
	v_lshlrev_b32_e32 v246, 16, v186
	v_and_b32_e32 v247, 0xffff0000, v186
	v_lshlrev_b32_e32 v248, 16, v187
	v_and_b32_e32 v249, 0xffff0000, v187
	v_fmac_f32_e32 v80, v118, v246
	v_fmac_f32_e32 v81, v118, v247
	v_fmac_f32_e32 v82, v118, v248
	v_fmac_f32_e32 v83, v118, v249
	v_mul_f32_e32 v246, 0xbfb8aa3b, v96
	v_mul_f32_e32 v247, 0xbfb8aa3b, v97
	v_mul_f32_e32 v248, 0xbfb8aa3b, v98
	v_mul_f32_e32 v249, 0xbfb8aa3b, v99
	v_exp_f32_e32 v246, v246
	v_exp_f32_e32 v247, v247
	v_exp_f32_e32 v248, v248
	v_exp_f32_e32 v249, v249
	v_add_f32_e32 v246, 1.0, v246
	v_add_f32_e32 v247, 1.0, v247
	v_add_f32_e32 v248, 1.0, v248
	v_add_f32_e32 v249, 1.0, v249
	v_rcp_f32_e32 v246, v246
	v_rcp_f32_e32 v247, v247
	v_rcp_f32_e32 v248, v248
	v_rcp_f32_e32 v249, v249
	v_mul_f32_e32 v96, v96, v246
	v_mul_f32_e32 v97, v97, v247
	v_mul_f32_e32 v98, v98, v248
	v_mul_f32_e32 v99, v99, v249
	v_mul_f32_e32 v80, v80, v96
	v_mul_f32_e32 v81, v81, v97
	v_mul_f32_e32 v82, v82, v98
	v_mul_f32_e32 v83, v83, v99
	v_cvt_pk_bf16_f32 v80, v80, v80
	v_cvt_pk_bf16_f32 v81, v81, v81
	v_cvt_pk_bf16_f32 v82, v82, v82
	v_cvt_pk_bf16_f32 v83, v83, v83
	global_store_short v[100:101], v80, off offset:-4096
	global_store_short v[100:101], v81, off
	global_store_short v[102:103], v82, off offset:-4096
	global_store_short v[102:103], v83, off
	v_and_b32_e32 v246, 0xffff0000, v80
	v_and_b32_e32 v247, 0xffff0000, v81
	v_and_b32_e32 v248, 0xffff0000, v82
	v_and_b32_e32 v249, 0xffff0000, v83
	v_mul_f32_e32 v96, v246, v246
	v_mul_f32_e32 v97, v247, v247
	v_mul_f32_e32 v98, v248, v248
	v_mul_f32_e32 v99, v249, v249
	s_waitcnt vmcnt(28)
	v_lshlrev_b32_e32 v119, 16, v119
	v_lshlrev_b32_e32 v120, 16, v120
	v_lshlrev_b32_e32 v121, 16, v121
	v_lshlrev_b32_e32 v122, 16, v122
	v_lshlrev_b32_e32 v246, 16, v188
	v_and_b32_e32 v247, 0xffff0000, v188
	v_lshlrev_b32_e32 v248, 16, v189
	v_and_b32_e32 v249, 0xffff0000, v189
	v_fmac_f32_e32 v84, v118, v246
	v_fmac_f32_e32 v85, v118, v247
	v_fmac_f32_e32 v86, v118, v248
	v_fmac_f32_e32 v87, v118, v249
	v_mul_f32_e32 v246, 0xbfb8aa3b, v119
	v_mul_f32_e32 v247, 0xbfb8aa3b, v120
	v_mul_f32_e32 v248, 0xbfb8aa3b, v121
	v_mul_f32_e32 v249, 0xbfb8aa3b, v122
	v_exp_f32_e32 v246, v246
	v_exp_f32_e32 v247, v247
	v_exp_f32_e32 v248, v248
	v_exp_f32_e32 v249, v249
	v_add_f32_e32 v246, 1.0, v246
	v_add_f32_e32 v247, 1.0, v247
	v_add_f32_e32 v248, 1.0, v248
	v_add_f32_e32 v249, 1.0, v249
	v_rcp_f32_e32 v246, v246
	v_rcp_f32_e32 v247, v247
	v_rcp_f32_e32 v248, v248
	v_rcp_f32_e32 v249, v249
	v_mul_f32_e32 v119, v119, v246
	v_mul_f32_e32 v120, v120, v247
	v_mul_f32_e32 v121, v121, v248
	v_mul_f32_e32 v122, v122, v249
	v_mul_f32_e32 v84, v84, v119
	v_mul_f32_e32 v85, v85, v120
	v_mul_f32_e32 v86, v86, v121
	v_mul_f32_e32 v87, v87, v122
	v_cvt_pk_bf16_f32 v84, v84, v84
	v_cvt_pk_bf16_f32 v85, v85, v85
	v_cvt_pk_bf16_f32 v86, v86, v86
	v_cvt_pk_bf16_f32 v87, v87, v87
	global_store_short v[104:105], v84, off offset:-4096
	global_store_short v[104:105], v85, off
	global_store_short v[106:107], v86, off offset:-4096
	global_store_short v[106:107], v87, off
	v_and_b32_e32 v246, 0xffff0000, v84
	v_and_b32_e32 v247, 0xffff0000, v85
	v_and_b32_e32 v248, 0xffff0000, v86
	v_and_b32_e32 v249, 0xffff0000, v87
	v_mul_f32_e32 v119, v246, v246
	v_mul_f32_e32 v120, v247, v247
	v_mul_f32_e32 v121, v248, v248
	v_mul_f32_e32 v122, v249, v249
	s_waitcnt vmcnt(28)
	v_lshlrev_b32_e32 v123, 16, v123
	v_lshlrev_b32_e32 v124, 16, v124
	v_lshlrev_b32_e32 v125, 16, v125
	v_lshlrev_b32_e32 v126, 16, v126
	v_lshlrev_b32_e32 v246, 16, v190
	v_and_b32_e32 v247, 0xffff0000, v190
	v_lshlrev_b32_e32 v248, 16, v191
	v_and_b32_e32 v249, 0xffff0000, v191
	v_fmac_f32_e32 v88, v118, v246
	v_fmac_f32_e32 v89, v118, v247
	v_fmac_f32_e32 v90, v118, v248
	v_fmac_f32_e32 v91, v118, v249
	v_mul_f32_e32 v246, 0xbfb8aa3b, v123
	v_mul_f32_e32 v247, 0xbfb8aa3b, v124
	v_mul_f32_e32 v248, 0xbfb8aa3b, v125
	v_mul_f32_e32 v249, 0xbfb8aa3b, v126
	v_exp_f32_e32 v246, v246
	v_exp_f32_e32 v247, v247
	v_exp_f32_e32 v248, v248
	v_exp_f32_e32 v249, v249
	v_add_f32_e32 v246, 1.0, v246
	v_add_f32_e32 v247, 1.0, v247
	v_add_f32_e32 v248, 1.0, v248
	v_add_f32_e32 v249, 1.0, v249
	v_rcp_f32_e32 v246, v246
	v_rcp_f32_e32 v247, v247
	v_rcp_f32_e32 v248, v248
	v_rcp_f32_e32 v249, v249
	v_mul_f32_e32 v123, v123, v246
	v_mul_f32_e32 v124, v124, v247
	v_mul_f32_e32 v125, v125, v248
	v_mul_f32_e32 v126, v126, v249
	v_mul_f32_e32 v88, v88, v123
	v_mul_f32_e32 v89, v89, v124
	v_mul_f32_e32 v90, v90, v125
	v_mul_f32_e32 v91, v91, v126
	v_cvt_pk_bf16_f32 v88, v88, v88
	v_cvt_pk_bf16_f32 v89, v89, v89
	v_cvt_pk_bf16_f32 v90, v90, v90
	v_cvt_pk_bf16_f32 v91, v91, v91
	global_store_short v[108:109], v88, off offset:-4096
	global_store_short v[108:109], v89, off
	global_store_short v[110:111], v90, off offset:-4096
	global_store_short v[110:111], v91, off
	v_and_b32_e32 v246, 0xffff0000, v88
	v_and_b32_e32 v247, 0xffff0000, v89
	v_and_b32_e32 v248, 0xffff0000, v90
	v_and_b32_e32 v249, 0xffff0000, v91
	v_mul_f32_e32 v123, v246, v246
	v_mul_f32_e32 v124, v247, v247
	v_mul_f32_e32 v125, v248, v248
	v_mul_f32_e32 v126, v249, v249
	s_waitcnt vmcnt(28)
	v_lshlrev_b32_e32 v127, 16, v127
	v_lshlrev_b32_e32 v212, 16, v212
	v_lshlrev_b32_e32 v213, 16, v213
	v_lshlrev_b32_e32 v214, 16, v214
	v_lshlrev_b32_e32 v246, 16, v192
	v_and_b32_e32 v247, 0xffff0000, v192
	v_lshlrev_b32_e32 v248, 16, v193
	v_and_b32_e32 v249, 0xffff0000, v193
	v_fmac_f32_e32 v92, v118, v246
	v_fmac_f32_e32 v93, v118, v247
	v_fmac_f32_e32 v94, v118, v248
	v_fmac_f32_e32 v95, v118, v249
	v_mul_f32_e32 v246, 0xbfb8aa3b, v127
	v_mul_f32_e32 v247, 0xbfb8aa3b, v212
	v_mul_f32_e32 v248, 0xbfb8aa3b, v213
	v_mul_f32_e32 v249, 0xbfb8aa3b, v214
	v_exp_f32_e32 v246, v246
	v_exp_f32_e32 v247, v247
	v_exp_f32_e32 v248, v248
	v_exp_f32_e32 v249, v249
	v_add_f32_e32 v246, 1.0, v246
	v_add_f32_e32 v247, 1.0, v247
	v_add_f32_e32 v248, 1.0, v248
	v_add_f32_e32 v249, 1.0, v249
	v_rcp_f32_e32 v246, v246
	v_rcp_f32_e32 v247, v247
	v_rcp_f32_e32 v248, v248
	v_rcp_f32_e32 v249, v249
	v_mul_f32_e32 v127, v127, v246
	v_mul_f32_e32 v212, v212, v247
	v_mul_f32_e32 v213, v213, v248
	v_mul_f32_e32 v214, v214, v249
	v_mul_f32_e32 v92, v92, v127
	v_mul_f32_e32 v93, v93, v212
	v_mul_f32_e32 v94, v94, v213
	v_mul_f32_e32 v95, v95, v214
	v_cvt_pk_bf16_f32 v92, v92, v92
	v_cvt_pk_bf16_f32 v93, v93, v93
	v_cvt_pk_bf16_f32 v94, v94, v94
	v_cvt_pk_bf16_f32 v95, v95, v95
	global_store_short v[114:115], v92, off offset:-4096
	global_store_short v[114:115], v93, off
	global_store_short v[116:117], v94, off offset:-4096
	global_store_short v[116:117], v95, off
	v_and_b32_e32 v246, 0xffff0000, v92
	v_and_b32_e32 v247, 0xffff0000, v93
	v_and_b32_e32 v248, 0xffff0000, v94
	v_and_b32_e32 v249, 0xffff0000, v95
	v_mul_f32_e32 v127, v246, v246
	v_mul_f32_e32 v212, v247, v247
	v_mul_f32_e32 v213, v248, v248
	v_mul_f32_e32 v214, v249, v249
	s_waitcnt vmcnt(28)
	v_lshlrev_b32_e32 v215, 16, v215
	v_lshlrev_b32_e32 v222, 16, v222
	v_lshlrev_b32_e32 v223, 16, v223
	v_lshlrev_b32_e32 v224, 16, v224
	v_lshlrev_b32_e32 v246, 16, v194
	v_and_b32_e32 v247, 0xffff0000, v194
	v_lshlrev_b32_e32 v248, 16, v195
	v_and_b32_e32 v249, 0xffff0000, v195
	v_fmac_f32_e32 v64, v118, v246
	v_fmac_f32_e32 v65, v118, v247
	v_fmac_f32_e32 v66, v118, v248
	v_fmac_f32_e32 v67, v118, v249
	v_mul_f32_e32 v246, 0xbfb8aa3b, v215
	v_mul_f32_e32 v247, 0xbfb8aa3b, v222
	v_mul_f32_e32 v248, 0xbfb8aa3b, v223
	v_mul_f32_e32 v249, 0xbfb8aa3b, v224
	v_exp_f32_e32 v246, v246
	v_exp_f32_e32 v247, v247
	v_exp_f32_e32 v248, v248
	v_exp_f32_e32 v249, v249
	v_add_f32_e32 v246, 1.0, v246
	v_add_f32_e32 v247, 1.0, v247
	v_add_f32_e32 v248, 1.0, v248
	v_add_f32_e32 v249, 1.0, v249
	v_rcp_f32_e32 v246, v246
	v_rcp_f32_e32 v247, v247
	v_rcp_f32_e32 v248, v248
	v_rcp_f32_e32 v249, v249
	v_mul_f32_e32 v215, v215, v246
	v_mul_f32_e32 v222, v222, v247
	v_mul_f32_e32 v223, v223, v248
	v_mul_f32_e32 v224, v224, v249
	v_mul_f32_e32 v64, v64, v215
	v_mul_f32_e32 v65, v65, v222
	v_mul_f32_e32 v66, v66, v223
	v_mul_f32_e32 v67, v67, v224
	v_cvt_pk_bf16_f32 v64, v64, v64
	v_cvt_pk_bf16_f32 v65, v65, v65
	v_cvt_pk_bf16_f32 v66, v66, v66
	v_cvt_pk_bf16_f32 v67, v67, v67
	global_store_short v[100:101], v64, off offset:-4032
	global_store_short v[100:101], v65, off offset:64
	global_store_short v[102:103], v66, off offset:-4032
	global_store_short v[102:103], v67, off offset:64
	v_and_b32_e32 v246, 0xffff0000, v64
	v_and_b32_e32 v247, 0xffff0000, v65
	v_and_b32_e32 v248, 0xffff0000, v66
	v_and_b32_e32 v249, 0xffff0000, v67
	v_fmac_f32_e32 v96, v246, v246
	v_fmac_f32_e32 v97, v247, v247
	v_fmac_f32_e32 v98, v248, v248
	v_fmac_f32_e32 v99, v249, v249
	s_waitcnt vmcnt(28)
	v_lshlrev_b32_e32 v225, 16, v225
	v_lshlrev_b32_e32 v234, 16, v234
	v_lshlrev_b32_e32 v235, 16, v235
	v_lshlrev_b32_e32 v236, 16, v236
	v_lshlrev_b32_e32 v246, 16, v196
	v_and_b32_e32 v247, 0xffff0000, v196
	v_lshlrev_b32_e32 v248, 16, v197
	v_and_b32_e32 v249, 0xffff0000, v197
	v_fmac_f32_e32 v68, v118, v246
	v_fmac_f32_e32 v69, v118, v247
	v_fmac_f32_e32 v70, v118, v248
	v_fmac_f32_e32 v71, v118, v249
	v_mul_f32_e32 v246, 0xbfb8aa3b, v225
	v_mul_f32_e32 v247, 0xbfb8aa3b, v234
	v_mul_f32_e32 v248, 0xbfb8aa3b, v235
	v_mul_f32_e32 v249, 0xbfb8aa3b, v236
	v_exp_f32_e32 v246, v246
	v_exp_f32_e32 v247, v247
	v_exp_f32_e32 v248, v248
	v_exp_f32_e32 v249, v249
	v_add_f32_e32 v246, 1.0, v246
	v_add_f32_e32 v247, 1.0, v247
	v_add_f32_e32 v248, 1.0, v248
	v_add_f32_e32 v249, 1.0, v249
	v_rcp_f32_e32 v246, v246
	v_rcp_f32_e32 v247, v247
	v_rcp_f32_e32 v248, v248
	v_rcp_f32_e32 v249, v249
	v_mul_f32_e32 v225, v225, v246
	v_mul_f32_e32 v234, v234, v247
	v_mul_f32_e32 v235, v235, v248
	v_mul_f32_e32 v236, v236, v249
	v_mul_f32_e32 v68, v68, v225
	v_mul_f32_e32 v69, v69, v234
	v_mul_f32_e32 v70, v70, v235
	v_mul_f32_e32 v71, v71, v236
	v_cvt_pk_bf16_f32 v68, v68, v68
	v_cvt_pk_bf16_f32 v69, v69, v69
	v_cvt_pk_bf16_f32 v70, v70, v70
	v_cvt_pk_bf16_f32 v71, v71, v71
	global_store_short v[104:105], v68, off offset:-4032
	global_store_short v[104:105], v69, off offset:64
	global_store_short v[106:107], v70, off offset:-4032
	global_store_short v[106:107], v71, off offset:64
	v_and_b32_e32 v246, 0xffff0000, v68
	v_and_b32_e32 v247, 0xffff0000, v69
	v_and_b32_e32 v248, 0xffff0000, v70
	v_and_b32_e32 v249, 0xffff0000, v71
	v_fmac_f32_e32 v119, v246, v246
	v_fmac_f32_e32 v120, v247, v247
	v_fmac_f32_e32 v121, v248, v248
	v_fmac_f32_e32 v122, v249, v249
	s_waitcnt vmcnt(28)
	v_lshlrev_b32_e32 v237, 16, v237
	v_lshlrev_b32_e32 v238, 16, v238
	v_lshlrev_b32_e32 v239, 16, v239
	v_lshlrev_b32_e32 v240, 16, v240
	v_lshlrev_b32_e32 v246, 16, v206
	v_and_b32_e32 v247, 0xffff0000, v206
	v_lshlrev_b32_e32 v248, 16, v207
	v_and_b32_e32 v249, 0xffff0000, v207
	v_fmac_f32_e32 v72, v118, v246
	v_fmac_f32_e32 v73, v118, v247
	v_fmac_f32_e32 v74, v118, v248
	v_fmac_f32_e32 v75, v118, v249
	v_mul_f32_e32 v246, 0xbfb8aa3b, v237
	v_mul_f32_e32 v247, 0xbfb8aa3b, v238
	v_mul_f32_e32 v248, 0xbfb8aa3b, v239
	v_mul_f32_e32 v249, 0xbfb8aa3b, v240
	v_exp_f32_e32 v246, v246
	v_exp_f32_e32 v247, v247
	v_exp_f32_e32 v248, v248
	v_exp_f32_e32 v249, v249
	v_add_f32_e32 v246, 1.0, v246
	v_add_f32_e32 v247, 1.0, v247
	v_add_f32_e32 v248, 1.0, v248
	v_add_f32_e32 v249, 1.0, v249
	v_rcp_f32_e32 v246, v246
	v_rcp_f32_e32 v247, v247
	v_rcp_f32_e32 v248, v248
	v_rcp_f32_e32 v249, v249
	v_mul_f32_e32 v237, v237, v246
	v_mul_f32_e32 v238, v238, v247
	v_mul_f32_e32 v239, v239, v248
	v_mul_f32_e32 v240, v240, v249
	v_mul_f32_e32 v72, v72, v237
	v_mul_f32_e32 v73, v73, v238
	v_mul_f32_e32 v74, v74, v239
	v_mul_f32_e32 v75, v75, v240
	v_cvt_pk_bf16_f32 v72, v72, v72
	v_cvt_pk_bf16_f32 v73, v73, v73
	v_cvt_pk_bf16_f32 v74, v74, v74
	v_cvt_pk_bf16_f32 v75, v75, v75
	global_store_short v[108:109], v72, off offset:-4032
	global_store_short v[108:109], v73, off offset:64
	global_store_short v[110:111], v74, off offset:-4032
	global_store_short v[110:111], v75, off offset:64
	v_and_b32_e32 v246, 0xffff0000, v72
	v_and_b32_e32 v247, 0xffff0000, v73
	v_and_b32_e32 v248, 0xffff0000, v74
	v_and_b32_e32 v249, 0xffff0000, v75
	v_fmac_f32_e32 v123, v246, v246
	v_fmac_f32_e32 v124, v247, v247
	v_fmac_f32_e32 v125, v248, v248
	v_fmac_f32_e32 v126, v249, v249
	s_waitcnt vmcnt(28)
	v_lshlrev_b32_e32 v241, 16, v241
	v_lshlrev_b32_e32 v242, 16, v242
	v_lshlrev_b32_e32 v243, 16, v243
	v_lshlrev_b32_e32 v244, 16, v244
	v_lshlrev_b32_e32 v246, 16, v208
	v_and_b32_e32 v247, 0xffff0000, v208
	v_lshlrev_b32_e32 v248, 16, v209
	v_and_b32_e32 v249, 0xffff0000, v209
	v_fmac_f32_e32 v76, v118, v246
	v_fmac_f32_e32 v77, v118, v247
	v_fmac_f32_e32 v78, v118, v248
	v_fmac_f32_e32 v79, v118, v249
	v_mul_f32_e32 v246, 0xbfb8aa3b, v241
	v_mul_f32_e32 v247, 0xbfb8aa3b, v242
	v_mul_f32_e32 v248, 0xbfb8aa3b, v243
	v_mul_f32_e32 v249, 0xbfb8aa3b, v244
	v_exp_f32_e32 v246, v246
	v_exp_f32_e32 v247, v247
	v_exp_f32_e32 v248, v248
	v_exp_f32_e32 v249, v249
	v_add_f32_e32 v246, 1.0, v246
	v_add_f32_e32 v247, 1.0, v247
	v_add_f32_e32 v248, 1.0, v248
	v_add_f32_e32 v249, 1.0, v249
	v_rcp_f32_e32 v246, v246
	v_rcp_f32_e32 v247, v247
	v_rcp_f32_e32 v248, v248
	v_rcp_f32_e32 v249, v249
	v_mul_f32_e32 v241, v241, v246
	v_mul_f32_e32 v242, v242, v247
	v_mul_f32_e32 v243, v243, v248
	v_mul_f32_e32 v244, v244, v249
	v_mul_f32_e32 v76, v76, v241
	v_mul_f32_e32 v77, v77, v242
	v_mul_f32_e32 v78, v78, v243
	v_mul_f32_e32 v79, v79, v244
	v_cvt_pk_bf16_f32 v76, v76, v76
	v_cvt_pk_bf16_f32 v77, v77, v77
	v_cvt_pk_bf16_f32 v78, v78, v78
	v_cvt_pk_bf16_f32 v79, v79, v79
	global_store_short v[114:115], v76, off offset:-4032
	global_store_short v[114:115], v77, off offset:64
	global_store_short v[116:117], v78, off offset:-4032
	global_store_short v[116:117], v79, off offset:64
	v_and_b32_e32 v246, 0xffff0000, v76
	v_and_b32_e32 v247, 0xffff0000, v77
	v_and_b32_e32 v248, 0xffff0000, v78
	v_and_b32_e32 v249, 0xffff0000, v79
	v_fmac_f32_e32 v127, v246, v246
	v_fmac_f32_e32 v212, v247, v247
	v_fmac_f32_e32 v213, v248, v248
	v_fmac_f32_e32 v214, v249, v249
	v_add_f32_dpp v96, v96, v96 row_shr:1 row_mask:0xf bank_mask:0xf
	v_add_f32_dpp v97, v97, v97 row_shr:1 row_mask:0xf bank_mask:0xf
	v_add_f32_dpp v98, v98, v98 row_shr:1 row_mask:0xf bank_mask:0xf
	v_add_f32_dpp v99, v99, v99 row_shr:1 row_mask:0xf bank_mask:0xf
	v_add_f32_dpp v119, v119, v119 row_shr:1 row_mask:0xf bank_mask:0xf
	v_add_f32_dpp v120, v120, v120 row_shr:1 row_mask:0xf bank_mask:0xf
	v_add_f32_dpp v121, v121, v121 row_shr:1 row_mask:0xf bank_mask:0xf
	v_add_f32_dpp v122, v122, v122 row_shr:1 row_mask:0xf bank_mask:0xf
	v_add_f32_dpp v123, v123, v123 row_shr:1 row_mask:0xf bank_mask:0xf
	v_add_f32_dpp v124, v124, v124 row_shr:1 row_mask:0xf bank_mask:0xf
	v_add_f32_dpp v125, v125, v125 row_shr:1 row_mask:0xf bank_mask:0xf
	v_add_f32_dpp v126, v126, v126 row_shr:1 row_mask:0xf bank_mask:0xf
	v_add_f32_dpp v127, v127, v127 row_shr:1 row_mask:0xf bank_mask:0xf
	v_add_f32_dpp v212, v212, v212 row_shr:1 row_mask:0xf bank_mask:0xf
	v_add_f32_dpp v213, v213, v213 row_shr:1 row_mask:0xf bank_mask:0xf
	v_add_f32_dpp v214, v214, v214 row_shr:1 row_mask:0xf bank_mask:0xf
	v_add_f32_dpp v96, v96, v96 row_shr:2 row_mask:0xf bank_mask:0xf
	v_add_f32_dpp v97, v97, v97 row_shr:2 row_mask:0xf bank_mask:0xf
	v_add_f32_dpp v98, v98, v98 row_shr:2 row_mask:0xf bank_mask:0xf
	v_add_f32_dpp v99, v99, v99 row_shr:2 row_mask:0xf bank_mask:0xf
	v_add_f32_dpp v119, v119, v119 row_shr:2 row_mask:0xf bank_mask:0xf
	v_add_f32_dpp v120, v120, v120 row_shr:2 row_mask:0xf bank_mask:0xf
	v_add_f32_dpp v121, v121, v121 row_shr:2 row_mask:0xf bank_mask:0xf
	v_add_f32_dpp v122, v122, v122 row_shr:2 row_mask:0xf bank_mask:0xf
	v_add_f32_dpp v123, v123, v123 row_shr:2 row_mask:0xf bank_mask:0xf
	v_add_f32_dpp v124, v124, v124 row_shr:2 row_mask:0xf bank_mask:0xf
	v_add_f32_dpp v125, v125, v125 row_shr:2 row_mask:0xf bank_mask:0xf
	v_add_f32_dpp v126, v126, v126 row_shr:2 row_mask:0xf bank_mask:0xf
	v_add_f32_dpp v127, v127, v127 row_shr:2 row_mask:0xf bank_mask:0xf
	v_add_f32_dpp v212, v212, v212 row_shr:2 row_mask:0xf bank_mask:0xf
	v_add_f32_dpp v213, v213, v213 row_shr:2 row_mask:0xf bank_mask:0xf
	v_add_f32_dpp v214, v214, v214 row_shr:2 row_mask:0xf bank_mask:0xf
	v_add_f32_dpp v96, v96, v96 row_shr:4 row_mask:0xf bank_mask:0xf
	v_add_f32_dpp v97, v97, v97 row_shr:4 row_mask:0xf bank_mask:0xf
	v_add_f32_dpp v98, v98, v98 row_shr:4 row_mask:0xf bank_mask:0xf
	v_add_f32_dpp v99, v99, v99 row_shr:4 row_mask:0xf bank_mask:0xf
	v_add_f32_dpp v119, v119, v119 row_shr:4 row_mask:0xf bank_mask:0xf
	v_add_f32_dpp v120, v120, v120 row_shr:4 row_mask:0xf bank_mask:0xf
	v_add_f32_dpp v121, v121, v121 row_shr:4 row_mask:0xf bank_mask:0xf
	v_add_f32_dpp v122, v122, v122 row_shr:4 row_mask:0xf bank_mask:0xf
	v_add_f32_dpp v123, v123, v123 row_shr:4 row_mask:0xf bank_mask:0xf
	v_add_f32_dpp v124, v124, v124 row_shr:4 row_mask:0xf bank_mask:0xf
	v_add_f32_dpp v125, v125, v125 row_shr:4 row_mask:0xf bank_mask:0xf
	v_add_f32_dpp v126, v126, v126 row_shr:4 row_mask:0xf bank_mask:0xf
	v_add_f32_dpp v127, v127, v127 row_shr:4 row_mask:0xf bank_mask:0xf
	v_add_f32_dpp v212, v212, v212 row_shr:4 row_mask:0xf bank_mask:0xf
	v_add_f32_dpp v213, v213, v213 row_shr:4 row_mask:0xf bank_mask:0xf
	v_add_f32_dpp v214, v214, v214 row_shr:4 row_mask:0xf bank_mask:0xf
	v_add_f32_dpp v96, v96, v96 row_shr:8 row_mask:0xf bank_mask:0xf
	v_add_f32_dpp v97, v97, v97 row_shr:8 row_mask:0xf bank_mask:0xf
	v_add_f32_dpp v98, v98, v98 row_shr:8 row_mask:0xf bank_mask:0xf
	v_add_f32_dpp v99, v99, v99 row_shr:8 row_mask:0xf bank_mask:0xf
	v_add_f32_dpp v119, v119, v119 row_shr:8 row_mask:0xf bank_mask:0xf
	v_add_f32_dpp v120, v120, v120 row_shr:8 row_mask:0xf bank_mask:0xf
	v_add_f32_dpp v121, v121, v121 row_shr:8 row_mask:0xf bank_mask:0xf
	v_add_f32_dpp v122, v122, v122 row_shr:8 row_mask:0xf bank_mask:0xf
	v_add_f32_dpp v123, v123, v123 row_shr:8 row_mask:0xf bank_mask:0xf
	v_add_f32_dpp v124, v124, v124 row_shr:8 row_mask:0xf bank_mask:0xf
	v_add_f32_dpp v125, v125, v125 row_shr:8 row_mask:0xf bank_mask:0xf
	v_add_f32_dpp v126, v126, v126 row_shr:8 row_mask:0xf bank_mask:0xf
	v_add_f32_dpp v127, v127, v127 row_shr:8 row_mask:0xf bank_mask:0xf
	v_add_f32_dpp v212, v212, v212 row_shr:8 row_mask:0xf bank_mask:0xf
	v_add_f32_dpp v213, v213, v213 row_shr:8 row_mask:0xf bank_mask:0xf
	v_add_f32_dpp v214, v214, v214 row_shr:8 row_mask:0xf bank_mask:0xf
	v_add_f32_dpp v96, v96, v96 row_bcast:15 row_mask:0xa bank_mask:0xf
	v_add_f32_dpp v97, v97, v97 row_bcast:15 row_mask:0xa bank_mask:0xf
	v_add_f32_dpp v98, v98, v98 row_bcast:15 row_mask:0xa bank_mask:0xf
	v_add_f32_dpp v99, v99, v99 row_bcast:15 row_mask:0xa bank_mask:0xf
	v_add_f32_dpp v119, v119, v119 row_bcast:15 row_mask:0xa bank_mask:0xf
	v_add_f32_dpp v120, v120, v120 row_bcast:15 row_mask:0xa bank_mask:0xf
	v_add_f32_dpp v121, v121, v121 row_bcast:15 row_mask:0xa bank_mask:0xf
	v_add_f32_dpp v122, v122, v122 row_bcast:15 row_mask:0xa bank_mask:0xf
	v_add_f32_dpp v123, v123, v123 row_bcast:15 row_mask:0xa bank_mask:0xf
	v_add_f32_dpp v124, v124, v124 row_bcast:15 row_mask:0xa bank_mask:0xf
	v_add_f32_dpp v125, v125, v125 row_bcast:15 row_mask:0xa bank_mask:0xf
	v_add_f32_dpp v126, v126, v126 row_bcast:15 row_mask:0xa bank_mask:0xf
	v_add_f32_dpp v127, v127, v127 row_bcast:15 row_mask:0xa bank_mask:0xf
	v_add_f32_dpp v212, v212, v212 row_bcast:15 row_mask:0xa bank_mask:0xf
	v_add_f32_dpp v213, v213, v213 row_bcast:15 row_mask:0xa bank_mask:0xf
	v_add_f32_dpp v214, v214, v214 row_bcast:15 row_mask:0xa bank_mask:0xf
	v_readlane_b32 s100, v255, 49
	s_ashr_i32 s100, s100, 3
	s_lshl_b32 s100, s100, 14
	s_lshl_b32 s101, s22, 2
	s_add_u32 s14, s33, s100
	s_addc_u32 s15, s18, 0
	s_add_u32 s14, s14, s101
	s_addc_u32 s15, s15, 0
	s_add_u32 s14, s14, 0x18d0b600
	s_addc_u32 s15, s15, 0
	v_lshlrev_b32_e32 v245, 7, v200
	s_mov_b32 exec_lo, 0x80000000
	s_mov_b32 exec_hi, 0x80000000
	global_store_dword v245, v96, s[14:15]
	global_store_dword v245, v97, s[14:15] offset:128
	global_store_dword v245, v98, s[14:15] offset:256
	global_store_dword v245, v99, s[14:15] offset:384
	global_store_dword v245, v119, s[14:15] offset:1024
	global_store_dword v245, v120, s[14:15] offset:1152
	global_store_dword v245, v121, s[14:15] offset:1280
	global_store_dword v245, v122, s[14:15] offset:1408
	global_store_dword v245, v123, s[14:15] offset:2048
	global_store_dword v245, v124, s[14:15] offset:2176
	global_store_dword v245, v125, s[14:15] offset:2304
	global_store_dword v245, v126, s[14:15] offset:2432
	global_store_dword v245, v127, s[14:15] offset:3072
	global_store_dword v245, v212, s[14:15] offset:3200
	global_store_dword v245, v213, s[14:15] offset:3328
	global_store_dword v245, v214, s[14:15] offset:3456
	s_mov_b64 exec, -1
	s_cmp_eq_u32 s19, 4
	s_cbranch_scc1 .LBB0_2100

.LBB0_2166:
	s_or_b64 exec, exec, s[0:1]
	s_mov_b64 s[4:5], s[60:61]
	v_mov_b32_e32 v1, v218
	s_waitcnt lgkmcnt(0)
	v_mov_b32_e32 v0, v219
	s_barrier
	s_mov_b64 s[0:1], exec
	s_branch .LBB0_2223
	s_movk_i32 s1, 0x4000
	v_readfirstlane_b32 s0, v0
	v_mov_b32_e32 v0, v218
	s_lshl_b32 s0, s0, 2
	v_ashrrev_i32_e32 v0, 6, v0
	v_add_u32_e32 v4, s0, v0
	v_cmp_gt_i32_e32 vcc, s1, v4
	s_and_saveexec_b64 s[2:3], vcc
	s_cbranch_execz .LBB0_2171
	s_load_dwordx2 s[4:5], s[4:5], 0xe8
	v_and_b32_e32 v5, 63, v1
	v_ashrrev_i32_e32 v1, 31, v0
	s_ashr_i32 s1, s0, 31
	v_lshl_add_u64 v[2:3], v[0:1], 0, s[0:1]
	s_waitcnt lgkmcnt(0)
	v_lshl_add_u64 v[0:1], v[2:3], 2, s[4:5]
	s_mov_b64 s[0:1], 0xf8000
	v_lshl_add_u64 v[0:1], v[0:1], 0, s[0:1]
	v_lshlrev_b64 v[2:3], 12, v[2:3]
	v_readlane_b32 s0, v252, 39
	v_lshl_or_b32 v2, v5, 4, v2
	v_readlane_b32 s1, v252, 40
	v_cmp_eq_u32_e32 vcc, 0, v5
	s_mov_b64 s[4:5], 0
	v_lshl_add_u64 v[2:3], s[0:1], 0, v[2:3]
	s_mov_b64 s[0:1], 0x5210800
	v_lshl_add_u64 v[2:3], v[2:3], 0, s[0:1]
	s_branch .LBB0_2169

.LBB0_2225:
	s_and_b32 s6, s2, 7
	v_lshl_add_u32 v0, s6, 8, v201
	v_ashrrev_i32_e32 v1, 31, v0
	v_lshlrev_b64 v[0:1], 12, v[0:1]
	s_and_b32 s6, s5, 0xffffff00
	v_lshl_add_u64 v[170:171], v[160:161], 0, v[0:1]
	v_add_u32_e32 v0, s6, v175
	s_and_b32 s6, s4, 7
	v_ashrrev_i32_e32 v1, 31, v0
	s_or_b32 s6, s6, s3
	v_lshlrev_b64 v[0:1], 12, v[0:1]
	s_lshl_b32 s6, s6, 8
	v_lshl_add_u64 v[172:173], v[168:169], 0, v[0:1]
	v_add_u32_e32 v0, s6, v175
	s_lshl_b32 s7, s4, 5
	v_ashrrev_i32_e32 v1, 31, v0
	s_and_b32 s7, s7, 0xffffff00
	v_add_u32_e32 v2, s7, v175
	v_lshlrev_b64 v[0:1], 12, v[0:1]
	s_waitcnt vmcnt(0) lgkmcnt(0)
	s_barrier
	v_and_b32_e32 v238, 0xff, v163
	v_add_u32_e32 v239, s6, v238
	v_lshlrev_b32_e32 v239, 7, v239
	v_add_u32_e32 v239, 0x1911b600, v239
	global_load_dwordx4 v[64:67], v239, s[0:1]
	global_load_dwordx4 v[68:71], v239, s[0:1] offset:16
	global_load_dwordx4 v[72:75], v239, s[0:1] offset:32
	global_load_dwordx4 v[76:79], v239, s[0:1] offset:48
	global_load_dwordx4 v[80:83], v239, s[0:1] offset:64
	global_load_dwordx4 v[84:87], v239, s[0:1] offset:80
	global_load_dwordx4 v[88:91], v239, s[0:1] offset:96
	global_load_dwordx4 v[92:95], v239, s[0:1] offset:112
	v_lshlrev_b32_e32 v238, 2, v238
	v_add_u32_e32 v238, 0x20020, v238
	v_mov_b32_e32 v250, 0x20020
	v_ashrrev_i32_e32 v3, 31, v2
	v_lshl_add_u64 v[0:1], v[154:155], 0, v[0:1]
	v_readfirstlane_b32 s8, v180
	s_mov_b32 m0, s8
	s_nop 0
	global_load_lds_dwordx4 v[0:1], off
	s_mov_b64 s[12:13], 0x80000
	v_lshlrev_b64 v[2:3], 12, v[2:3]
	v_lshl_add_u64 v[4:5], v[0:1], 0, s[12:13]
	s_add_i32 s9, s8, 0x2000
	s_mov_b32 m0, s9
	s_nop 0
	global_load_lds_dwordx4 v[4:5], off
	v_lshl_add_u64 v[2:3], v[156:157], 0, v[2:3]
	s_add_i32 s9, s8, 0x4000
	s_mov_b32 m0, s9
	s_nop 0
	global_load_lds_dwordx4 v[2:3], off
	v_lshl_add_u64 v[4:5], v[2:3], 0, s[12:13]
	s_add_i32 s9, s8, 0x6000
	s_mov_b32 m0, s9
	s_nop 0
	global_load_lds_dwordx4 v[4:5], off
	s_add_i32 s9, s8, 0x8000
	v_lshl_add_u64 v[4:5], v[0:1], 0, 64
	s_mov_b32 m0, s9
	s_nop 0
	global_load_lds_dwordx4 v[4:5], off
	s_mov_b64 s[10:11], 0x80040
	v_lshl_add_u64 v[4:5], v[0:1], 0, s[10:11]
	s_add_i32 s9, s8, 0xa000
	s_mov_b32 m0, s9
	s_nop 0
	global_load_lds_dwordx4 v[4:5], off
	v_lshl_add_u64 v[4:5], v[2:3], 0, 64
	s_add_i32 s9, s8, 0xc000
	s_mov_b32 m0, s9
	s_nop 0
	global_load_lds_dwordx4 v[4:5], off
	v_lshl_add_u64 v[4:5], v[2:3], 0, s[10:11]
	s_add_i32 s9, s8, 0xe000
	s_mov_b32 m0, s9
	s_nop 0
	global_load_lds_dwordx4 v[4:5], off
	s_mov_b64 s[10:11], 0x80
	s_add_i32 s9, s8, 0x10000
	v_lshl_add_u64 v[4:5], v[0:1], 0, s[10:11]
	s_mov_b32 m0, s9
	s_nop 0
	global_load_lds_dwordx4 v[4:5], off
	s_mov_b64 s[14:15], 0x80080
	v_lshl_add_u64 v[0:1], v[0:1], 0, s[14:15]
	s_add_i32 s9, s8, 0x12000
	s_mov_b32 m0, s9
	s_nop 0
	global_load_lds_dwordx4 v[0:1], off
	v_lshl_add_u64 v[0:1], v[2:3], 0, s[10:11]
	s_add_i32 s9, s8, 0x14000
	s_mov_b32 m0, s9
	s_nop 0
	global_load_lds_dwordx4 v[0:1], off
	v_lshl_add_u64 v[0:1], v[2:3], 0, s[14:15]
	s_add_i32 s8, s8, 0x16000
	s_mov_b32 m0, s8
	s_nop 0
	global_load_lds_dwordx4 v[0:1], off
	s_waitcnt vmcnt(12)
	v_add_f32_e32 v64, v64, v65
	v_add_f32_e32 v64, v64, v66
	v_add_f32_e32 v64, v64, v67
	v_add_f32_e32 v64, v64, v68
	v_add_f32_e32 v64, v64, v69
	v_add_f32_e32 v64, v64, v70
	v_add_f32_e32 v64, v64, v71
	v_add_f32_e32 v64, v64, v72
	v_add_f32_e32 v64, v64, v73
	v_add_f32_e32 v64, v64, v74
	v_add_f32_e32 v64, v64, v75
	v_add_f32_e32 v64, v64, v76
	v_add_f32_e32 v64, v64, v77
	v_add_f32_e32 v64, v64, v78
	v_add_f32_e32 v64, v64, v79
	v_add_f32_e32 v64, v64, v80
	v_add_f32_e32 v64, v64, v81
	v_add_f32_e32 v64, v64, v82
	v_add_f32_e32 v64, v64, v83
	v_add_f32_e32 v64, v64, v84
	v_add_f32_e32 v64, v64, v85
	v_add_f32_e32 v64, v64, v86
	v_add_f32_e32 v64, v64, v87
	v_add_f32_e32 v64, v64, v88
	v_add_f32_e32 v64, v64, v89
	v_add_f32_e32 v64, v64, v90
	v_add_f32_e32 v64, v64, v91
	v_add_f32_e32 v64, v64, v92
	v_add_f32_e32 v64, v64, v93
	v_add_f32_e32 v64, v64, v94
	v_add_f32_e32 v64, v64, v95
	v_fmamk_f32 v64, v64, 0x3a000000, v162
	v_mul_f32_e32 v65, 0x4b800000, v64
	v_cmp_gt_f32_e32 vcc, 0x800000, v64
	s_nop 1
	v_cndmask_b32_e32 v64, v64, v65, vcc
	v_rsq_f32_e32 v64, v64
	s_nop 0
	v_mul_f32_e32 v65, 0x45800000, v64
	v_cndmask_b32_e32 v64, v64, v65, vcc
	ds_write_b32 v238, v64
	v_mov_b32_e32 v130, 0
	v_mov_b32_e32 v134, 0
	v_mov_b32_e32 v0, 0
	s_mov_b32 s8, 0x18000
	v_mov_b32_e32 v1, v0
	v_mov_b32_e32 v2, v0
	v_mov_b32_e32 v3, v0
	v_mov_b32_e32 v4, v0
	v_mov_b32_e32 v5, v0
	v_mov_b32_e32 v6, v0
	v_mov_b32_e32 v7, v0
	v_mov_b32_e32 v8, v0
	v_mov_b32_e32 v9, v0
	v_mov_b32_e32 v10, v0
	v_mov_b32_e32 v11, v0
	v_mov_b32_e32 v12, v0
	v_mov_b32_e32 v13, v0
	v_mov_b32_e32 v14, v0
	v_mov_b32_e32 v15, v0
	v_mov_b32_e32 v16, v0
	v_mov_b32_e32 v17, v0
	v_mov_b32_e32 v18, v0
	v_mov_b32_e32 v19, v0
	v_mov_b32_e32 v20, v0
	v_mov_b32_e32 v21, v0
	v_mov_b32_e32 v22, v0
	v_mov_b32_e32 v23, v0
	v_mov_b32_e32 v24, v0
	v_mov_b32_e32 v25, v0
	v_mov_b32_e32 v26, v0
	v_mov_b32_e32 v27, v0
	v_mov_b32_e32 v28, v0
	v_mov_b32_e32 v29, v0
	v_mov_b32_e32 v30, v0
	v_mov_b32_e32 v31, v0
	v_mov_b32_e32 v32, v0
	v_mov_b32_e32 v33, v0
	v_mov_b32_e32 v34, v0
	v_mov_b32_e32 v35, v0
	v_mov_b32_e32 v36, v0
	v_mov_b32_e32 v37, v0
	v_mov_b32_e32 v38, v0
	v_mov_b32_e32 v39, v0
	v_mov_b32_e32 v40, v0
	v_mov_b32_e32 v41, v0
	v_mov_b32_e32 v42, v0
	v_mov_b32_e32 v43, v0
	v_mov_b32_e32 v44, v0
	v_mov_b32_e32 v45, v0
	v_mov_b32_e32 v46, v0
	v_mov_b32_e32 v47, v0
	v_mov_b32_e32 v48, v0
	v_mov_b32_e32 v49, v0
	v_mov_b32_e32 v50, v0
	v_mov_b32_e32 v51, v0
	v_mov_b32_e32 v52, v0
	v_mov_b32_e32 v53, v0
	v_mov_b32_e32 v54, v0
	v_mov_b32_e32 v55, v0
	v_mov_b32_e32 v56, v0
	v_mov_b32_e32 v57, v0
	v_mov_b32_e32 v58, v0
	v_mov_b32_e32 v59, v0
	v_mov_b32_e32 v60, v0
	v_mov_b32_e32 v61, v0
	v_mov_b32_e32 v62, v0
	v_mov_b32_e32 v63, v0
	v_mov_b32_e32 v64, v0
	v_mov_b32_e32 v65, v0
	v_mov_b32_e32 v66, v0
	v_mov_b32_e32 v67, v0
	v_mov_b32_e32 v68, v0
	v_mov_b32_e32 v69, v0
	v_mov_b32_e32 v70, v0
	v_mov_b32_e32 v71, v0
	v_mov_b32_e32 v72, v0
	v_mov_b32_e32 v73, v0
	v_mov_b32_e32 v74, v0
	v_mov_b32_e32 v75, v0
	v_mov_b32_e32 v76, v0
	v_mov_b32_e32 v77, v0
	v_mov_b32_e32 v78, v0
	v_mov_b32_e32 v79, v0
	v_mov_b32_e32 v80, v0
	v_mov_b32_e32 v81, v0
	v_mov_b32_e32 v82, v0
	v_mov_b32_e32 v83, v0
	v_mov_b32_e32 v84, v0
	v_mov_b32_e32 v85, v0
	v_mov_b32_e32 v86, v0
	v_mov_b32_e32 v87, v0
	v_mov_b32_e32 v88, v0
	v_mov_b32_e32 v89, v0
	v_mov_b32_e32 v90, v0
	v_mov_b32_e32 v91, v0
	v_mov_b32_e32 v92, v0
	v_mov_b32_e32 v93, v0
	v_mov_b32_e32 v94, v0
	v_mov_b32_e32 v95, v0
	v_mov_b32_e32 v96, v0
	v_mov_b32_e32 v97, v0
	v_mov_b32_e32 v98, v0
	v_mov_b32_e32 v99, v0
	v_mov_b32_e32 v100, v0
	v_mov_b32_e32 v101, v0
	v_mov_b32_e32 v102, v0
	v_mov_b32_e32 v103, v0
	v_mov_b32_e32 v104, v0
	v_mov_b32_e32 v105, v0
	v_mov_b32_e32 v106, v0
	v_mov_b32_e32 v107, v0
	v_mov_b32_e32 v108, v0
	v_mov_b32_e32 v109, v0
	v_mov_b32_e32 v110, v0
	v_mov_b32_e32 v111, v0
	v_mov_b32_e32 v112, v0
	v_mov_b32_e32 v113, v0
	v_mov_b32_e32 v114, v0
	v_mov_b32_e32 v115, v0
	v_mov_b32_e32 v116, v0
	v_mov_b32_e32 v117, v0
	v_mov_b32_e32 v118, v0
	v_mov_b32_e32 v119, v0
	v_mov_b32_e32 v120, v0
	v_mov_b32_e32 v121, v0
	v_mov_b32_e32 v122, v0
	v_mov_b32_e32 v123, v0
	v_mov_b32_e32 v124, v0
	v_mov_b32_e32 v125, v0
	v_mov_b32_e32 v126, v0
	v_mov_b32_e32 v127, v0
	v_mov_b32_e32 v135, v134
	v_mov_b32_e32 v136, v134
	v_mov_b32_e32 v137, v134
	v_mov_b32_e32 v138, v134
	v_mov_b32_e32 v139, v134
	v_mov_b32_e32 v140, v134
	v_mov_b32_e32 v141, v134
	v_mov_b32_e32 v146, v134
	v_mov_b32_e32 v147, v134
	v_mov_b32_e32 v148, v134
	v_mov_b32_e32 v149, v134
	v_mov_b32_e32 v150, v134
	v_mov_b32_e32 v151, v134
	v_mov_b32_e32 v152, v134
	v_mov_b32_e32 v153, v134
	v_mov_b32_e32 v131, v130
	v_mov_b32_e32 v132, v130
	v_mov_b32_e32 v133, v130
	v_mov_b32_e32 v142, v130
	v_mov_b32_e32 v143, v130
	v_mov_b32_e32 v144, v130
	v_mov_b32_e32 v145, v130
